# stack of all individually validated edits: v30 + S5-C B-fragment read pipelining + GEMM k-inner MFMA order + GEMM loop-edge rotation + scalar-base K/V prefetch addressing in the attention loop
# speedup vs baseline: 1.0087x; 1.0051x over previous
.LBB0_540:
	s_add_u32 s22, s18, s20
	s_addc_u32 s23, s19, s21
	s_add_u32 s22, s22, 0x100
	s_addc_u32 s23, s23, 0
	s_add_u32 s49, s40, s20
	s_addc_u32 s56, s41, s21
	s_add_i32 s58, 0, 0x10000
	s_cmpk_eq_i32 s20, 0x700
	s_cselect_b32 s23, s15, s23
	s_cselect_b32 s22, s14, s22
	v_add_u32_e32 v149, s58, v147
	s_cselect_b32 s57, s17, s56
	s_cselect_b32 s56, s16, s49
	s_add_i32 s49, 0, 0x14000
	ds_read_b128 v[150:153], v149
	ds_read_b128 v[154:157], v149 offset:1024
	ds_read_b128 v[158:161], v149 offset:2048
	ds_read_b128 v[162:165], v149 offset:3072
	v_add_u32_e32 v149, s49, v147
	ds_read_b128 v[166:169], v149
	ds_read_b128 v[170:173], v149 offset:1024
	ds_read_b128 v[174:177], v149 offset:2048
	ds_read_b128 v[178:181], v149 offset:3072
	v_lshl_add_u64 v[220:221], v[142:143], 0, s[20:21]
	s_add_i32 m0, s27, 0xc000
	ds_read_b128 v[182:185], v148
	ds_read_b128 v[186:189], v148 offset:1024
	ds_read_b128 v[204:207], v148 offset:2048
	ds_read_b128 v[208:211], v148 offset:3072
	ds_read_b128 v[212:215], v148 offset:4096
	ds_read_b128 v[216:219], v148 offset:5120
	ds_read_b128 v[230:233], v148 offset:6144
	ds_read_b128 v[234:237], v148 offset:7168
	global_load_lds_dwordx4 v[220:221], off
	v_lshl_add_u64 v[220:221], v[144:145], 0, s[20:21]
	s_add_i32 m0, s27, 0xe000
	s_nop 0
	global_load_lds_dwordx4 v[220:221], off
	s_waitcnt vmcnt(8)
	s_waitcnt lgkmcnt(0)
	s_barrier
	s_setprio 1
	s_waitcnt lgkmcnt(0)
	v_mfma_f32_16x16x32_bf16 v[126:129], v[150:153], v[182:185], v[126:129]
	v_mfma_f32_16x16x32_bf16 v[126:129], v[154:157], v[186:189], v[126:129]
	v_mfma_f32_16x16x32_bf16 v[118:121], v[158:161], v[182:185], v[118:121]
	v_mfma_f32_16x16x32_bf16 v[118:121], v[162:165], v[186:189], v[118:121]
	v_mfma_f32_16x16x32_bf16 v[110:113], v[150:153], v[204:207], v[110:113]
	v_mfma_f32_16x16x32_bf16 v[110:113], v[154:157], v[208:211], v[110:113]
	v_mfma_f32_16x16x32_bf16 v[102:105], v[158:161], v[204:207], v[102:105]
	v_mfma_f32_16x16x32_bf16 v[102:105], v[162:165], v[208:211], v[102:105]
	v_mfma_f32_16x16x32_bf16 v[94:97], v[150:153], v[212:215], v[94:97]
	v_mfma_f32_16x16x32_bf16 v[94:97], v[154:157], v[216:219], v[94:97]
	v_mfma_f32_16x16x32_bf16 v[86:89], v[158:161], v[212:215], v[86:89]
	v_mfma_f32_16x16x32_bf16 v[86:89], v[162:165], v[216:219], v[86:89]
	v_mfma_f32_16x16x32_bf16 v[78:81], v[150:153], v[230:233], v[78:81]
	v_mfma_f32_16x16x32_bf16 v[78:81], v[154:157], v[234:237], v[78:81]
	v_mfma_f32_16x16x32_bf16 v[70:73], v[158:161], v[230:233], v[70:73]
	v_mfma_f32_16x16x32_bf16 v[70:73], v[162:165], v[234:237], v[70:73]
	s_setprio 0
	s_setprio 1
	v_mfma_f32_16x16x32_bf16 v[122:125], v[166:169], v[182:185], v[122:125]
	v_mfma_f32_16x16x32_bf16 v[122:125], v[170:173], v[186:189], v[122:125]
	v_mfma_f32_16x16x32_bf16 v[114:117], v[174:177], v[182:185], v[114:117]
	v_mfma_f32_16x16x32_bf16 v[114:117], v[178:181], v[186:189], v[114:117]
	v_mfma_f32_16x16x32_bf16 v[106:109], v[166:169], v[204:207], v[106:109]
	v_mfma_f32_16x16x32_bf16 v[106:109], v[170:173], v[208:211], v[106:109]
	v_mfma_f32_16x16x32_bf16 v[98:101], v[174:177], v[204:207], v[98:101]
	v_mfma_f32_16x16x32_bf16 v[98:101], v[178:181], v[208:211], v[98:101]
	v_mfma_f32_16x16x32_bf16 v[90:93], v[166:169], v[212:215], v[90:93]
	v_mfma_f32_16x16x32_bf16 v[90:93], v[170:173], v[216:219], v[90:93]
	v_mfma_f32_16x16x32_bf16 v[82:85], v[174:177], v[212:215], v[82:85]
	v_mfma_f32_16x16x32_bf16 v[82:85], v[178:181], v[216:219], v[82:85]
	v_mfma_f32_16x16x32_bf16 v[74:77], v[166:169], v[230:233], v[74:77]
	v_mfma_f32_16x16x32_bf16 v[74:77], v[170:173], v[234:237], v[74:77]
	v_mfma_f32_16x16x32_bf16 v[66:69], v[174:177], v[230:233], v[66:69]
	v_mfma_f32_16x16x32_bf16 v[66:69], v[178:181], v[234:237], v[66:69]
	s_setprio 0
	s_barrier
	s_add_i32 s58, s58, s25
	v_lshl_add_u64 v[220:221], s[56:57], 0, v[134:135]
	s_mov_b32 m0, s58
	ds_read_b128 v[182:185], v148 offset:16384
	ds_read_b128 v[186:189], v148 offset:17408
	ds_read_b128 v[204:207], v148 offset:18432
	ds_read_b128 v[208:211], v148 offset:19456
	ds_read_b128 v[212:215], v148 offset:20480
	ds_read_b128 v[216:219], v148 offset:21504
	ds_read_b128 v[230:233], v148 offset:22528
	ds_read_b128 v[234:237], v148 offset:23552
	global_load_lds_dwordx4 v[220:221], off
	s_add_i32 m0, s58, 0x2000
	v_lshl_add_u64 v[238:239], s[56:57], 0, v[130:131]
	s_add_u32 s56, s56, s4
	s_addc_u32 s57, s57, s5
	s_add_i32 s49, s49, s25
	global_load_lds_dwordx4 v[238:239], off
	v_lshl_add_u64 v[240:241], s[56:57], 0, v[134:135]
	s_mov_b32 m0, s49
	v_lshl_add_u64 v[242:243], s[56:57], 0, v[130:131]
	global_load_lds_dwordx4 v[240:241], off
	s_add_i32 m0, s49, 0x2000
	v_lshl_add_u64 v[244:245], s[22:23], 0, v[136:137]
	global_load_lds_dwordx4 v[242:243], off
	s_mov_b32 m0, s27
	v_lshl_add_u64 v[246:247], s[22:23], 0, v[132:133]
	global_load_lds_dwordx4 v[244:245], off
	s_mov_b32 m0, s28
	s_nop 0
	global_load_lds_dwordx4 v[246:247], off
	s_waitcnt vmcnt(8)
	s_waitcnt lgkmcnt(0)
	s_barrier
	s_setprio 1
	s_waitcnt lgkmcnt(0)
	v_mfma_f32_16x16x32_bf16 v[62:65], v[150:153], v[182:185], v[62:65]
	v_mfma_f32_16x16x32_bf16 v[62:65], v[154:157], v[186:189], v[62:65]
	v_mfma_f32_16x16x32_bf16 v[54:57], v[158:161], v[182:185], v[54:57]
	v_mfma_f32_16x16x32_bf16 v[54:57], v[162:165], v[186:189], v[54:57]
	v_mfma_f32_16x16x32_bf16 v[46:49], v[150:153], v[204:207], v[46:49]
	v_mfma_f32_16x16x32_bf16 v[46:49], v[154:157], v[208:211], v[46:49]
	v_mfma_f32_16x16x32_bf16 v[38:41], v[158:161], v[204:207], v[38:41]
	v_mfma_f32_16x16x32_bf16 v[38:41], v[162:165], v[208:211], v[38:41]
	v_mfma_f32_16x16x32_bf16 v[30:33], v[150:153], v[212:215], v[30:33]
	v_mfma_f32_16x16x32_bf16 v[30:33], v[154:157], v[216:219], v[30:33]
	v_mfma_f32_16x16x32_bf16 v[22:25], v[158:161], v[212:215], v[22:25]
	v_mfma_f32_16x16x32_bf16 v[22:25], v[162:165], v[216:219], v[22:25]
	v_mfma_f32_16x16x32_bf16 v[14:17], v[150:153], v[230:233], v[14:17]
	v_mfma_f32_16x16x32_bf16 v[14:17], v[154:157], v[234:237], v[14:17]
	v_mfma_f32_16x16x32_bf16 v[6:9], v[158:161], v[230:233], v[6:9]
	v_mfma_f32_16x16x32_bf16 v[6:9], v[162:165], v[234:237], v[6:9]
	s_setprio 0
	s_setprio 1
	v_mfma_f32_16x16x32_bf16 v[58:61], v[166:169], v[182:185], v[58:61]
	v_mfma_f32_16x16x32_bf16 v[58:61], v[170:173], v[186:189], v[58:61]
	v_mfma_f32_16x16x32_bf16 v[50:53], v[174:177], v[182:185], v[50:53]
	v_mfma_f32_16x16x32_bf16 v[50:53], v[178:181], v[186:189], v[50:53]
	v_mfma_f32_16x16x32_bf16 v[42:45], v[166:169], v[204:207], v[42:45]
	v_mfma_f32_16x16x32_bf16 v[42:45], v[170:173], v[208:211], v[42:45]
	v_mfma_f32_16x16x32_bf16 v[34:37], v[174:177], v[204:207], v[34:37]
	v_mfma_f32_16x16x32_bf16 v[34:37], v[178:181], v[208:211], v[34:37]
	v_mfma_f32_16x16x32_bf16 v[26:29], v[166:169], v[212:215], v[26:29]
	v_mfma_f32_16x16x32_bf16 v[26:29], v[170:173], v[216:219], v[26:29]
	v_mfma_f32_16x16x32_bf16 v[18:21], v[174:177], v[212:215], v[18:21]
	v_mfma_f32_16x16x32_bf16 v[18:21], v[178:181], v[216:219], v[18:21]
	v_mfma_f32_16x16x32_bf16 v[10:13], v[166:169], v[230:233], v[10:13]
	v_mfma_f32_16x16x32_bf16 v[10:13], v[170:173], v[234:237], v[10:13]
	v_mfma_f32_16x16x32_bf16 v[2:5], v[174:177], v[230:233], v[2:5]
	v_mfma_f32_16x16x32_bf16 v[2:5], v[178:181], v[234:237], v[2:5]
	s_setprio 0
	s_barrier
	s_add_i32 s49, 0, 0x18000
	v_add_u32_e32 v149, s49, v147
	s_add_i32 s56, 0, 0x1c000
	ds_read_b128 v[150:153], v149
	ds_read_b128 v[154:157], v149 offset:1024
	ds_read_b128 v[158:161], v149 offset:2048
	ds_read_b128 v[162:165], v149 offset:3072
	v_add_u32_e32 v149, s56, v147
	ds_read_b128 v[166:169], v149
	ds_read_b128 v[170:173], v149 offset:1024
	ds_read_b128 v[174:177], v149 offset:2048
	ds_read_b128 v[178:181], v149 offset:3072
	s_add_u32 s22, s22, s4
	s_addc_u32 s23, s23, s5
	s_mov_b32 m0, s29
	v_lshl_add_u64 v[248:249], s[22:23], 0, v[136:137]
	ds_read_b128 v[182:185], v148 offset:32768
	ds_read_b128 v[186:189], v148 offset:33792
	ds_read_b128 v[204:207], v148 offset:34816
	ds_read_b128 v[208:211], v148 offset:35840
	ds_read_b128 v[212:215], v148 offset:36864
	ds_read_b128 v[216:219], v148 offset:37888
	ds_read_b128 v[230:233], v148 offset:38912
	ds_read_b128 v[234:237], v148 offset:39936
	global_load_lds_dwordx4 v[248:249], off
	v_lshl_add_u64 v[248:249], s[22:23], 0, v[132:133]
	s_mov_b32 m0, s30
	s_nop 0
	global_load_lds_dwordx4 v[248:249], off
	s_waitcnt vmcnt(8)
	s_waitcnt lgkmcnt(0)
	s_barrier
	s_setprio 1
	s_waitcnt lgkmcnt(0)
	v_mfma_f32_16x16x32_bf16 v[126:129], v[150:153], v[182:185], v[126:129]
	v_mfma_f32_16x16x32_bf16 v[126:129], v[154:157], v[186:189], v[126:129]
	v_mfma_f32_16x16x32_bf16 v[118:121], v[158:161], v[182:185], v[118:121]
	v_mfma_f32_16x16x32_bf16 v[118:121], v[162:165], v[186:189], v[118:121]
	v_mfma_f32_16x16x32_bf16 v[110:113], v[150:153], v[204:207], v[110:113]
	v_mfma_f32_16x16x32_bf16 v[110:113], v[154:157], v[208:211], v[110:113]
	v_mfma_f32_16x16x32_bf16 v[102:105], v[158:161], v[204:207], v[102:105]
	v_mfma_f32_16x16x32_bf16 v[102:105], v[162:165], v[208:211], v[102:105]
	v_mfma_f32_16x16x32_bf16 v[94:97], v[150:153], v[212:215], v[94:97]
	v_mfma_f32_16x16x32_bf16 v[94:97], v[154:157], v[216:219], v[94:97]
	v_mfma_f32_16x16x32_bf16 v[86:89], v[158:161], v[212:215], v[86:89]
	v_mfma_f32_16x16x32_bf16 v[86:89], v[162:165], v[216:219], v[86:89]
	v_mfma_f32_16x16x32_bf16 v[78:81], v[150:153], v[230:233], v[78:81]
	v_mfma_f32_16x16x32_bf16 v[78:81], v[154:157], v[234:237], v[78:81]
	v_mfma_f32_16x16x32_bf16 v[70:73], v[158:161], v[230:233], v[70:73]
	v_mfma_f32_16x16x32_bf16 v[70:73], v[162:165], v[234:237], v[70:73]
	s_setprio 0
	s_setprio 1
	v_mfma_f32_16x16x32_bf16 v[122:125], v[166:169], v[182:185], v[122:125]
	v_mfma_f32_16x16x32_bf16 v[122:125], v[170:173], v[186:189], v[122:125]
	v_mfma_f32_16x16x32_bf16 v[114:117], v[174:177], v[182:185], v[114:117]
	v_mfma_f32_16x16x32_bf16 v[114:117], v[178:181], v[186:189], v[114:117]
	v_mfma_f32_16x16x32_bf16 v[106:109], v[166:169], v[204:207], v[106:109]
	v_mfma_f32_16x16x32_bf16 v[106:109], v[170:173], v[208:211], v[106:109]
	v_mfma_f32_16x16x32_bf16 v[98:101], v[174:177], v[204:207], v[98:101]
	v_mfma_f32_16x16x32_bf16 v[98:101], v[178:181], v[208:211], v[98:101]
	v_mfma_f32_16x16x32_bf16 v[90:93], v[166:169], v[212:215], v[90:93]
	v_mfma_f32_16x16x32_bf16 v[90:93], v[170:173], v[216:219], v[90:93]
	v_mfma_f32_16x16x32_bf16 v[82:85], v[174:177], v[212:215], v[82:85]
	v_mfma_f32_16x16x32_bf16 v[82:85], v[178:181], v[216:219], v[82:85]
	v_mfma_f32_16x16x32_bf16 v[74:77], v[166:169], v[230:233], v[74:77]
	v_mfma_f32_16x16x32_bf16 v[74:77], v[170:173], v[234:237], v[74:77]
	v_mfma_f32_16x16x32_bf16 v[66:69], v[174:177], v[230:233], v[66:69]
	v_mfma_f32_16x16x32_bf16 v[66:69], v[178:181], v[234:237], v[66:69]
	s_setprio 0
	s_barrier
	s_add_i32 s22, s49, s25
	v_lshl_add_u64 v[220:221], v[220:221], 0, s[68:69]
	s_mov_b32 m0, s22
	ds_read_b128 v[182:185], v148 offset:49152
	ds_read_b128 v[186:189], v148 offset:50176
	ds_read_b128 v[204:207], v148 offset:51200
	ds_read_b128 v[208:211], v148 offset:52224
	ds_read_b128 v[212:215], v148 offset:53248
	ds_read_b128 v[216:219], v148 offset:54272
	ds_read_b128 v[230:233], v148 offset:55296
	ds_read_b128 v[234:237], v148 offset:56320
	global_load_lds_dwordx4 v[220:221], off
	v_lshl_add_u64 v[220:221], v[238:239], 0, s[68:69]
	s_add_i32 m0, s22, 0x2000
	s_add_i32 s22, s56, s25
	global_load_lds_dwordx4 v[220:221], off
	v_lshl_add_u64 v[220:221], v[240:241], 0, s[68:69]
	s_mov_b32 m0, s22
	s_nop 0
	global_load_lds_dwordx4 v[220:221], off
	v_lshl_add_u64 v[220:221], v[242:243], 0, s[68:69]
	s_add_i32 m0, s22, 0x2000
	s_nop 0
	global_load_lds_dwordx4 v[220:221], off
	v_lshl_add_u64 v[220:221], v[244:245], 0, s[68:69]
	s_mov_b32 m0, s31
	s_nop 0
	global_load_lds_dwordx4 v[220:221], off
	v_lshl_add_u64 v[220:221], v[246:247], 0, s[68:69]
	s_mov_b32 m0, s33
	s_nop 0
	global_load_lds_dwordx4 v[220:221], off
	s_waitcnt vmcnt(8)
	s_waitcnt lgkmcnt(0)
	s_barrier
	s_setprio 1
	s_waitcnt lgkmcnt(0)
	v_mfma_f32_16x16x32_bf16 v[62:65], v[150:153], v[182:185], v[62:65]
	v_mfma_f32_16x16x32_bf16 v[62:65], v[154:157], v[186:189], v[62:65]
	v_mfma_f32_16x16x32_bf16 v[54:57], v[158:161], v[182:185], v[54:57]
	v_mfma_f32_16x16x32_bf16 v[54:57], v[162:165], v[186:189], v[54:57]
	v_mfma_f32_16x16x32_bf16 v[46:49], v[150:153], v[204:207], v[46:49]
	v_mfma_f32_16x16x32_bf16 v[46:49], v[154:157], v[208:211], v[46:49]
	v_mfma_f32_16x16x32_bf16 v[38:41], v[158:161], v[204:207], v[38:41]
	v_mfma_f32_16x16x32_bf16 v[38:41], v[162:165], v[208:211], v[38:41]
	v_mfma_f32_16x16x32_bf16 v[30:33], v[150:153], v[212:215], v[30:33]
	v_mfma_f32_16x16x32_bf16 v[30:33], v[154:157], v[216:219], v[30:33]
	v_mfma_f32_16x16x32_bf16 v[22:25], v[158:161], v[212:215], v[22:25]
	v_mfma_f32_16x16x32_bf16 v[22:25], v[162:165], v[216:219], v[22:25]
	v_mfma_f32_16x16x32_bf16 v[14:17], v[150:153], v[230:233], v[14:17]
	v_mfma_f32_16x16x32_bf16 v[14:17], v[154:157], v[234:237], v[14:17]
	v_mfma_f32_16x16x32_bf16 v[6:9], v[158:161], v[230:233], v[6:9]
	v_mfma_f32_16x16x32_bf16 v[6:9], v[162:165], v[234:237], v[6:9]
	s_setprio 0
	s_setprio 1
	v_mfma_f32_16x16x32_bf16 v[58:61], v[166:169], v[182:185], v[58:61]
	v_mfma_f32_16x16x32_bf16 v[58:61], v[170:173], v[186:189], v[58:61]
	v_mfma_f32_16x16x32_bf16 v[50:53], v[174:177], v[182:185], v[50:53]
	v_mfma_f32_16x16x32_bf16 v[50:53], v[178:181], v[186:189], v[50:53]
	v_mfma_f32_16x16x32_bf16 v[42:45], v[166:169], v[204:207], v[42:45]
	v_mfma_f32_16x16x32_bf16 v[42:45], v[170:173], v[208:211], v[42:45]
	v_mfma_f32_16x16x32_bf16 v[34:37], v[174:177], v[204:207], v[34:37]
	v_mfma_f32_16x16x32_bf16 v[34:37], v[178:181], v[208:211], v[34:37]
	v_mfma_f32_16x16x32_bf16 v[26:29], v[166:169], v[212:215], v[26:29]
	v_mfma_f32_16x16x32_bf16 v[26:29], v[170:173], v[216:219], v[26:29]
	v_mfma_f32_16x16x32_bf16 v[18:21], v[174:177], v[212:215], v[18:21]
	v_mfma_f32_16x16x32_bf16 v[18:21], v[178:181], v[216:219], v[18:21]
	v_mfma_f32_16x16x32_bf16 v[10:13], v[166:169], v[230:233], v[10:13]
	v_mfma_f32_16x16x32_bf16 v[10:13], v[170:173], v[234:237], v[10:13]
	v_mfma_f32_16x16x32_bf16 v[2:5], v[174:177], v[230:233], v[2:5]
	v_mfma_f32_16x16x32_bf16 v[2:5], v[178:181], v[234:237], v[2:5]
	s_setprio 0
	s_add_i32 s48, s48, 2
	s_add_u32 s20, s20, 0x100
	s_addc_u32 s21, s21, 0
	s_cmp_gt_u32 s48, 13
	s_barrier
	s_cbranch_scc0 .LBB0_540
	s_and_b64 vcc, exec, s[12:13]
	s_cbranch_vccz .LBB0_543
	s_barrier

.LBB0_590:
	s_add_i32 s86, s26, 2
	s_add_u32 s74, s24, 0x80
	s_addc_u32 s27, s25, 0
	s_add_i32 s87, 0, 0x10000
	s_cmp_eq_u32 s19, s26
	s_cselect_b32 s27, s21, s27
	s_cselect_b32 s26, s20, s74
	v_add_u32_e32 v148, s87, v152
	s_cselect_b32 s75, s23, s29
	s_cselect_b32 s74, s22, s28
	s_add_i32 s88, 0, 0x14000
	ds_read_b128 v[130:133], v148
	ds_read_b128 v[144:147], v148 offset:1024
	ds_read_b128 v[154:157], v148 offset:2048
	ds_read_b128 v[158:161], v148 offset:3072
	v_add_u32_e32 v148, s88, v152
	ds_read_b128 v[162:165], v148
	ds_read_b128 v[166:169], v148 offset:1024
	ds_read_b128 v[170:173], v148 offset:2048
	ds_read_b128 v[174:177], v148 offset:3072
	v_lshl_add_u64 v[148:149], s[24:25], 0, v[140:141]
	s_add_i32 m0, s34, 0xc000
	ds_read_b128 v[178:181], v153
	ds_read_b128 v[182:185], v153 offset:1024
	ds_read_b128 v[186:189], v153 offset:2048
	ds_read_b128 v[204:207], v153 offset:3072
	ds_read_b128 v[208:211], v153 offset:4096
	ds_read_b128 v[212:215], v153 offset:5120
	ds_read_b128 v[216:219], v153 offset:6144
	ds_read_b128 v[230:233], v153 offset:7168
	global_load_lds_dwordx4 v[148:149], off
	v_lshl_add_u64 v[148:149], s[24:25], 0, v[142:143]
	s_add_i32 m0, s34, 0xe000
	s_nop 0
	global_load_lds_dwordx4 v[148:149], off
	s_waitcnt vmcnt(8)
	s_waitcnt lgkmcnt(0)
	s_barrier
	s_setprio 1
	s_waitcnt lgkmcnt(0)
	v_mfma_f32_16x16x32_bf16 v[126:129], v[130:133], v[178:181], v[126:129]
	v_mfma_f32_16x16x32_bf16 v[126:129], v[144:147], v[182:185], v[126:129]
	v_mfma_f32_16x16x32_bf16 v[122:125], v[154:157], v[178:181], v[122:125]
	v_mfma_f32_16x16x32_bf16 v[122:125], v[158:161], v[182:185], v[122:125]
	v_mfma_f32_16x16x32_bf16 v[110:113], v[130:133], v[186:189], v[110:113]
	v_mfma_f32_16x16x32_bf16 v[110:113], v[144:147], v[204:207], v[110:113]
	v_mfma_f32_16x16x32_bf16 v[106:109], v[154:157], v[186:189], v[106:109]
	v_mfma_f32_16x16x32_bf16 v[106:109], v[158:161], v[204:207], v[106:109]
	v_mfma_f32_16x16x32_bf16 v[94:97], v[130:133], v[208:211], v[94:97]
	v_mfma_f32_16x16x32_bf16 v[94:97], v[144:147], v[212:215], v[94:97]
	v_mfma_f32_16x16x32_bf16 v[90:93], v[154:157], v[208:211], v[90:93]
	v_mfma_f32_16x16x32_bf16 v[90:93], v[158:161], v[212:215], v[90:93]
	v_mfma_f32_16x16x32_bf16 v[78:81], v[130:133], v[216:219], v[78:81]
	v_mfma_f32_16x16x32_bf16 v[78:81], v[144:147], v[230:233], v[78:81]
	v_mfma_f32_16x16x32_bf16 v[74:77], v[154:157], v[216:219], v[74:77]
	v_mfma_f32_16x16x32_bf16 v[74:77], v[158:161], v[230:233], v[74:77]
	s_setprio 0
	s_setprio 1
	v_mfma_f32_16x16x32_bf16 v[118:121], v[162:165], v[178:181], v[118:121]
	v_mfma_f32_16x16x32_bf16 v[118:121], v[166:169], v[182:185], v[118:121]
	v_mfma_f32_16x16x32_bf16 v[114:117], v[170:173], v[178:181], v[114:117]
	v_mfma_f32_16x16x32_bf16 v[114:117], v[174:177], v[182:185], v[114:117]
	v_mfma_f32_16x16x32_bf16 v[102:105], v[162:165], v[186:189], v[102:105]
	v_mfma_f32_16x16x32_bf16 v[102:105], v[166:169], v[204:207], v[102:105]
	v_mfma_f32_16x16x32_bf16 v[98:101], v[170:173], v[186:189], v[98:101]
	v_mfma_f32_16x16x32_bf16 v[98:101], v[174:177], v[204:207], v[98:101]
	v_mfma_f32_16x16x32_bf16 v[86:89], v[162:165], v[208:211], v[86:89]
	v_mfma_f32_16x16x32_bf16 v[86:89], v[166:169], v[212:215], v[86:89]
	v_mfma_f32_16x16x32_bf16 v[82:85], v[170:173], v[208:211], v[82:85]
	v_mfma_f32_16x16x32_bf16 v[82:85], v[174:177], v[212:215], v[82:85]
	v_mfma_f32_16x16x32_bf16 v[70:73], v[162:165], v[216:219], v[70:73]
	v_mfma_f32_16x16x32_bf16 v[70:73], v[166:169], v[230:233], v[70:73]
	v_mfma_f32_16x16x32_bf16 v[66:69], v[170:173], v[216:219], v[66:69]
	v_mfma_f32_16x16x32_bf16 v[66:69], v[174:177], v[230:233], v[66:69]
	s_setprio 0
	s_barrier
	s_add_i32 s87, s87, s33
	v_lshl_add_u64 v[148:149], s[74:75], 0, v[190:191]
	s_mov_b32 m0, s87
	ds_read_b128 v[178:181], v153 offset:16384
	ds_read_b128 v[182:185], v153 offset:17408
	ds_read_b128 v[186:189], v153 offset:18432
	ds_read_b128 v[204:207], v153 offset:19456
	ds_read_b128 v[208:211], v153 offset:20480
	ds_read_b128 v[212:215], v153 offset:21504
	ds_read_b128 v[216:219], v153 offset:22528
	ds_read_b128 v[230:233], v153 offset:23552
	global_load_lds_dwordx4 v[148:149], off
	s_add_i32 m0, s87, 0x2000
	v_lshl_add_u64 v[220:221], s[74:75], 0, v[138:139]
	s_add_u32 s74, s74, s8
	s_addc_u32 s75, s75, s9
	s_add_i32 s87, s88, s33
	global_load_lds_dwordx4 v[220:221], off
	v_lshl_add_u64 v[234:235], s[74:75], 0, v[190:191]
	s_mov_b32 m0, s87
	v_lshl_add_u64 v[236:237], s[74:75], 0, v[138:139]
	global_load_lds_dwordx4 v[234:235], off
	s_add_i32 m0, s87, 0x2000
	v_lshl_add_u64 v[238:239], s[26:27], 0, v[134:135]
	global_load_lds_dwordx4 v[236:237], off
	s_mov_b32 m0, s34
	v_lshl_add_u64 v[240:241], s[26:27], 0, v[136:137]
	global_load_lds_dwordx4 v[238:239], off
	s_mov_b32 m0, s35
	s_nop 0
	global_load_lds_dwordx4 v[240:241], off
	s_waitcnt vmcnt(8)
	s_waitcnt lgkmcnt(0)
	s_barrier
	s_setprio 1
	s_waitcnt lgkmcnt(0)
	v_mfma_f32_16x16x32_bf16 v[62:65], v[130:133], v[178:181], v[62:65]
	v_mfma_f32_16x16x32_bf16 v[62:65], v[144:147], v[182:185], v[62:65]
	v_mfma_f32_16x16x32_bf16 v[58:61], v[154:157], v[178:181], v[58:61]
	v_mfma_f32_16x16x32_bf16 v[58:61], v[158:161], v[182:185], v[58:61]
	v_mfma_f32_16x16x32_bf16 v[46:49], v[130:133], v[186:189], v[46:49]
	v_mfma_f32_16x16x32_bf16 v[46:49], v[144:147], v[204:207], v[46:49]
	v_mfma_f32_16x16x32_bf16 v[42:45], v[154:157], v[186:189], v[42:45]
	v_mfma_f32_16x16x32_bf16 v[42:45], v[158:161], v[204:207], v[42:45]
	v_mfma_f32_16x16x32_bf16 v[30:33], v[130:133], v[208:211], v[30:33]
	v_mfma_f32_16x16x32_bf16 v[30:33], v[144:147], v[212:215], v[30:33]
	v_mfma_f32_16x16x32_bf16 v[26:29], v[154:157], v[208:211], v[26:29]
	v_mfma_f32_16x16x32_bf16 v[26:29], v[158:161], v[212:215], v[26:29]
	v_mfma_f32_16x16x32_bf16 v[14:17], v[130:133], v[216:219], v[14:17]
	v_mfma_f32_16x16x32_bf16 v[14:17], v[144:147], v[230:233], v[14:17]
	v_mfma_f32_16x16x32_bf16 v[10:13], v[154:157], v[216:219], v[10:13]
	v_mfma_f32_16x16x32_bf16 v[10:13], v[158:161], v[230:233], v[10:13]
	s_setprio 0
	s_setprio 1
	v_mfma_f32_16x16x32_bf16 v[54:57], v[162:165], v[178:181], v[54:57]
	v_mfma_f32_16x16x32_bf16 v[54:57], v[166:169], v[182:185], v[54:57]
	v_mfma_f32_16x16x32_bf16 v[50:53], v[170:173], v[178:181], v[50:53]
	v_mfma_f32_16x16x32_bf16 v[50:53], v[174:177], v[182:185], v[50:53]
	v_mfma_f32_16x16x32_bf16 v[38:41], v[162:165], v[186:189], v[38:41]
	v_mfma_f32_16x16x32_bf16 v[38:41], v[166:169], v[204:207], v[38:41]
	v_mfma_f32_16x16x32_bf16 v[34:37], v[170:173], v[186:189], v[34:37]
	v_mfma_f32_16x16x32_bf16 v[34:37], v[174:177], v[204:207], v[34:37]
	v_mfma_f32_16x16x32_bf16 v[22:25], v[162:165], v[208:211], v[22:25]
	v_mfma_f32_16x16x32_bf16 v[22:25], v[166:169], v[212:215], v[22:25]
	v_mfma_f32_16x16x32_bf16 v[18:21], v[170:173], v[208:211], v[18:21]
	v_mfma_f32_16x16x32_bf16 v[18:21], v[174:177], v[212:215], v[18:21]
	v_mfma_f32_16x16x32_bf16 v[6:9], v[162:165], v[216:219], v[6:9]
	v_mfma_f32_16x16x32_bf16 v[6:9], v[166:169], v[230:233], v[6:9]
	v_mfma_f32_16x16x32_bf16 v[2:5], v[170:173], v[216:219], v[2:5]
	v_mfma_f32_16x16x32_bf16 v[2:5], v[174:177], v[230:233], v[2:5]
	s_setprio 0
	s_barrier
	s_add_i32 s74, 0, 0x18000
	s_add_i32 s75, 0, 0x1c000
	v_add_u32_e32 v158, s74, v152
	v_add_u32_e32 v174, s75, v152
	ds_read_b128 v[130:133], v158
	ds_read_b128 v[144:147], v158 offset:1024
	ds_read_b128 v[154:157], v158 offset:2048
	ds_read_b128 v[158:161], v158 offset:3072
	ds_read_b128 v[162:165], v174
	ds_read_b128 v[166:169], v174 offset:1024
	ds_read_b128 v[170:173], v174 offset:2048
	ds_read_b128 v[174:177], v174 offset:3072
	s_add_u32 s26, s26, s8
	s_addc_u32 s27, s27, s9
	s_mov_b32 m0, s36
	v_lshl_add_u64 v[242:243], s[26:27], 0, v[134:135]
	ds_read_b128 v[178:181], v153 offset:32768
	ds_read_b128 v[182:185], v153 offset:33792
	ds_read_b128 v[186:189], v153 offset:34816
	ds_read_b128 v[204:207], v153 offset:35840
	ds_read_b128 v[208:211], v153 offset:36864
	ds_read_b128 v[212:215], v153 offset:37888
	ds_read_b128 v[216:219], v153 offset:38912
	ds_read_b128 v[230:233], v153 offset:39936
	global_load_lds_dwordx4 v[242:243], off
	v_lshl_add_u64 v[242:243], s[26:27], 0, v[136:137]
	s_mov_b32 m0, s37
	s_nop 0
	global_load_lds_dwordx4 v[242:243], off
	s_waitcnt vmcnt(8)
	s_waitcnt lgkmcnt(0)
	s_barrier
	s_setprio 1
	s_waitcnt lgkmcnt(0)
	v_mfma_f32_16x16x32_bf16 v[126:129], v[130:133], v[178:181], v[126:129]
	v_mfma_f32_16x16x32_bf16 v[126:129], v[144:147], v[182:185], v[126:129]
	v_mfma_f32_16x16x32_bf16 v[122:125], v[154:157], v[178:181], v[122:125]
	v_mfma_f32_16x16x32_bf16 v[122:125], v[158:161], v[182:185], v[122:125]
	v_mfma_f32_16x16x32_bf16 v[110:113], v[130:133], v[186:189], v[110:113]
	v_mfma_f32_16x16x32_bf16 v[110:113], v[144:147], v[204:207], v[110:113]
	v_mfma_f32_16x16x32_bf16 v[106:109], v[154:157], v[186:189], v[106:109]
	v_mfma_f32_16x16x32_bf16 v[106:109], v[158:161], v[204:207], v[106:109]
	v_mfma_f32_16x16x32_bf16 v[94:97], v[130:133], v[208:211], v[94:97]
	v_mfma_f32_16x16x32_bf16 v[94:97], v[144:147], v[212:215], v[94:97]
	v_mfma_f32_16x16x32_bf16 v[90:93], v[154:157], v[208:211], v[90:93]
	v_mfma_f32_16x16x32_bf16 v[90:93], v[158:161], v[212:215], v[90:93]
	v_mfma_f32_16x16x32_bf16 v[78:81], v[130:133], v[216:219], v[78:81]
	v_mfma_f32_16x16x32_bf16 v[78:81], v[144:147], v[230:233], v[78:81]
	v_mfma_f32_16x16x32_bf16 v[74:77], v[154:157], v[216:219], v[74:77]
	v_mfma_f32_16x16x32_bf16 v[74:77], v[158:161], v[230:233], v[74:77]
	s_setprio 0
	s_setprio 1
	v_mfma_f32_16x16x32_bf16 v[118:121], v[162:165], v[178:181], v[118:121]
	v_mfma_f32_16x16x32_bf16 v[118:121], v[166:169], v[182:185], v[118:121]
	v_mfma_f32_16x16x32_bf16 v[114:117], v[170:173], v[178:181], v[114:117]
	v_mfma_f32_16x16x32_bf16 v[114:117], v[174:177], v[182:185], v[114:117]
	v_mfma_f32_16x16x32_bf16 v[102:105], v[162:165], v[186:189], v[102:105]
	v_mfma_f32_16x16x32_bf16 v[102:105], v[166:169], v[204:207], v[102:105]
	v_mfma_f32_16x16x32_bf16 v[98:101], v[170:173], v[186:189], v[98:101]
	v_mfma_f32_16x16x32_bf16 v[98:101], v[174:177], v[204:207], v[98:101]
	v_mfma_f32_16x16x32_bf16 v[86:89], v[162:165], v[208:211], v[86:89]
	v_mfma_f32_16x16x32_bf16 v[86:89], v[166:169], v[212:215], v[86:89]
	v_mfma_f32_16x16x32_bf16 v[82:85], v[170:173], v[208:211], v[82:85]
	v_mfma_f32_16x16x32_bf16 v[82:85], v[174:177], v[212:215], v[82:85]
	v_mfma_f32_16x16x32_bf16 v[70:73], v[162:165], v[216:219], v[70:73]
	v_mfma_f32_16x16x32_bf16 v[70:73], v[166:169], v[230:233], v[70:73]
	v_mfma_f32_16x16x32_bf16 v[66:69], v[170:173], v[216:219], v[66:69]
	v_mfma_f32_16x16x32_bf16 v[66:69], v[174:177], v[230:233], v[66:69]
	s_setprio 0
	s_barrier
	s_add_i32 s26, s74, s33
	v_lshl_add_u64 v[148:149], v[148:149], 0, s[68:69]
	s_mov_b32 m0, s26
	ds_read_b128 v[178:181], v153 offset:49152
	ds_read_b128 v[182:185], v153 offset:50176
	ds_read_b128 v[186:189], v153 offset:51200
	ds_read_b128 v[204:207], v153 offset:52224
	ds_read_b128 v[208:211], v153 offset:53248
	ds_read_b128 v[212:215], v153 offset:54272
	ds_read_b128 v[216:219], v153 offset:55296
	ds_read_b128 v[230:233], v153 offset:56320
	global_load_lds_dwordx4 v[148:149], off
	v_lshl_add_u64 v[148:149], v[220:221], 0, s[68:69]
	s_add_i32 m0, s26, 0x2000
	s_add_i32 s26, s75, s33
	global_load_lds_dwordx4 v[148:149], off
	v_lshl_add_u64 v[148:149], v[234:235], 0, s[68:69]
	s_mov_b32 m0, s26
	s_nop 0
	global_load_lds_dwordx4 v[148:149], off
	v_lshl_add_u64 v[148:149], v[236:237], 0, s[68:69]
	s_add_i32 m0, s26, 0x2000
	s_nop 0
	global_load_lds_dwordx4 v[148:149], off
	v_lshl_add_u64 v[148:149], v[238:239], 0, s[68:69]
	s_mov_b32 m0, s72
	s_nop 0
	global_load_lds_dwordx4 v[148:149], off
	v_lshl_add_u64 v[148:149], v[240:241], 0, s[68:69]
	s_mov_b32 m0, s78
	s_nop 0
	global_load_lds_dwordx4 v[148:149], off
	s_waitcnt vmcnt(8)
	s_waitcnt lgkmcnt(0)
	s_barrier
	s_setprio 1
	s_waitcnt lgkmcnt(0)
	v_mfma_f32_16x16x32_bf16 v[62:65], v[130:133], v[178:181], v[62:65]
	v_mfma_f32_16x16x32_bf16 v[62:65], v[144:147], v[182:185], v[62:65]
	v_mfma_f32_16x16x32_bf16 v[58:61], v[154:157], v[178:181], v[58:61]
	v_mfma_f32_16x16x32_bf16 v[58:61], v[158:161], v[182:185], v[58:61]
	v_mfma_f32_16x16x32_bf16 v[46:49], v[130:133], v[186:189], v[46:49]
	v_mfma_f32_16x16x32_bf16 v[46:49], v[144:147], v[204:207], v[46:49]
	v_mfma_f32_16x16x32_bf16 v[42:45], v[154:157], v[186:189], v[42:45]
	v_mfma_f32_16x16x32_bf16 v[42:45], v[158:161], v[204:207], v[42:45]
	v_mfma_f32_16x16x32_bf16 v[30:33], v[130:133], v[208:211], v[30:33]
	v_mfma_f32_16x16x32_bf16 v[30:33], v[144:147], v[212:215], v[30:33]
	v_mfma_f32_16x16x32_bf16 v[26:29], v[154:157], v[208:211], v[26:29]
	v_mfma_f32_16x16x32_bf16 v[26:29], v[158:161], v[212:215], v[26:29]
	v_mfma_f32_16x16x32_bf16 v[14:17], v[130:133], v[216:219], v[14:17]
	v_mfma_f32_16x16x32_bf16 v[14:17], v[144:147], v[230:233], v[14:17]
	v_mfma_f32_16x16x32_bf16 v[10:13], v[154:157], v[216:219], v[10:13]
	v_mfma_f32_16x16x32_bf16 v[10:13], v[158:161], v[230:233], v[10:13]
	s_setprio 0
	s_setprio 1
	v_mfma_f32_16x16x32_bf16 v[54:57], v[162:165], v[178:181], v[54:57]
	v_mfma_f32_16x16x32_bf16 v[54:57], v[166:169], v[182:185], v[54:57]
	v_mfma_f32_16x16x32_bf16 v[50:53], v[170:173], v[178:181], v[50:53]
	v_mfma_f32_16x16x32_bf16 v[50:53], v[174:177], v[182:185], v[50:53]
	v_mfma_f32_16x16x32_bf16 v[38:41], v[162:165], v[186:189], v[38:41]
	v_mfma_f32_16x16x32_bf16 v[38:41], v[166:169], v[204:207], v[38:41]
	v_mfma_f32_16x16x32_bf16 v[34:37], v[170:173], v[186:189], v[34:37]
	v_mfma_f32_16x16x32_bf16 v[34:37], v[174:177], v[204:207], v[34:37]
	v_mfma_f32_16x16x32_bf16 v[22:25], v[162:165], v[208:211], v[22:25]
	v_mfma_f32_16x16x32_bf16 v[22:25], v[166:169], v[212:215], v[22:25]
	v_mfma_f32_16x16x32_bf16 v[18:21], v[170:173], v[208:211], v[18:21]
	v_mfma_f32_16x16x32_bf16 v[18:21], v[174:177], v[212:215], v[18:21]
	v_mfma_f32_16x16x32_bf16 v[6:9], v[162:165], v[216:219], v[6:9]
	v_mfma_f32_16x16x32_bf16 v[6:9], v[166:169], v[230:233], v[6:9]
	v_mfma_f32_16x16x32_bf16 v[2:5], v[170:173], v[216:219], v[2:5]
	v_mfma_f32_16x16x32_bf16 v[2:5], v[174:177], v[230:233], v[2:5]
	s_setprio 0
	s_add_u32 s24, s24, 0x100
	s_addc_u32 s25, s25, 0
	s_add_u32 s28, s28, 0x100
	s_addc_u32 s29, s29, 0
	s_cmp_ge_i32 s86, s85
	s_mov_b32 s26, s86
	s_barrier
	s_cbranch_scc0 .LBB0_590
	s_and_b64 vcc, exec, s[16:17]
	s_cbranch_vccz .LBB0_593
	s_barrier

.LBB0_1658:
	s_add_u32 s10, s34, s44
	s_addc_u32 s11, s35, s45
	s_add_u32 s10, s10, 0x100
	s_addc_u32 s11, s11, 0
	s_add_u32 s72, s33, s44
	s_addc_u32 s74, s48, s45
	s_add_i32 s75, 0, 0x10000
	s_cmpk_eq_i32 s44, 0x700
	s_cselect_b32 s11, s29, s11
	s_cselect_b32 s10, s28, s10
	s_cselect_b32 s81, s31, s74
	s_cselect_b32 s80, s30, s72
	s_add_i32 s72, 0, 0x14000
	v_add_u32_e32 v146, s75, v184
	v_add_u32_e32 v158, s72, v184
	ds_read_b128 v[134:137], v146
	ds_read_b128 v[138:141], v146 offset:1024
	ds_read_b128 v[142:145], v146 offset:2048
	ds_read_b128 v[146:149], v146 offset:3072
	ds_read_b128 v[150:153], v158
	ds_read_b128 v[154:157], v158 offset:1024
	ds_read_b128 v[178:181], v158 offset:2048
	ds_read_b128 v[186:189], v158 offset:3072
	v_lshl_add_u64 v[158:159], v[130:131], 0, s[44:45]
	s_add_i32 m0, s14, 0xc000
	ds_read_b128 v[204:207], v185
	ds_read_b128 v[208:211], v185 offset:1024
	ds_read_b128 v[212:215], v185 offset:2048
	ds_read_b128 v[216:219], v185 offset:3072
	ds_read_b128 v[226:229], v185 offset:4096
	ds_read_b128 v[230:233], v185 offset:5120
	ds_read_b128 v[234:237], v185 offset:6144
	ds_read_b128 v[238:241], v185 offset:7168
	global_load_lds_dwordx4 v[158:159], off
	v_lshl_add_u64 v[158:159], v[132:133], 0, s[44:45]
	s_add_i32 m0, s14, 0xe000
	s_nop 0
	global_load_lds_dwordx4 v[158:159], off
	s_waitcnt vmcnt(8)
	s_waitcnt lgkmcnt(0)
	s_barrier
	s_setprio 1
	s_waitcnt lgkmcnt(0)
	v_mfma_f32_16x16x32_bf16 v[126:129], v[134:137], v[204:207], v[126:129]
	v_mfma_f32_16x16x32_bf16 v[126:129], v[138:141], v[208:211], v[126:129]
	v_mfma_f32_16x16x32_bf16 v[122:125], v[142:145], v[204:207], v[122:125]
	v_mfma_f32_16x16x32_bf16 v[122:125], v[146:149], v[208:211], v[122:125]
	v_mfma_f32_16x16x32_bf16 v[110:113], v[134:137], v[212:215], v[110:113]
	v_mfma_f32_16x16x32_bf16 v[110:113], v[138:141], v[216:219], v[110:113]
	v_mfma_f32_16x16x32_bf16 v[106:109], v[142:145], v[212:215], v[106:109]
	v_mfma_f32_16x16x32_bf16 v[106:109], v[146:149], v[216:219], v[106:109]
	v_mfma_f32_16x16x32_bf16 v[94:97], v[134:137], v[226:229], v[94:97]
	v_mfma_f32_16x16x32_bf16 v[94:97], v[138:141], v[230:233], v[94:97]
	v_mfma_f32_16x16x32_bf16 v[90:93], v[142:145], v[226:229], v[90:93]
	v_mfma_f32_16x16x32_bf16 v[90:93], v[146:149], v[230:233], v[90:93]
	v_mfma_f32_16x16x32_bf16 v[78:81], v[134:137], v[234:237], v[78:81]
	v_mfma_f32_16x16x32_bf16 v[78:81], v[138:141], v[238:241], v[78:81]
	v_mfma_f32_16x16x32_bf16 v[74:77], v[142:145], v[234:237], v[74:77]
	v_mfma_f32_16x16x32_bf16 v[74:77], v[146:149], v[238:241], v[74:77]
	s_setprio 0
	s_setprio 1
	v_mfma_f32_16x16x32_bf16 v[118:121], v[150:153], v[204:207], v[118:121]
	v_mfma_f32_16x16x32_bf16 v[118:121], v[154:157], v[208:211], v[118:121]
	v_mfma_f32_16x16x32_bf16 v[114:117], v[178:181], v[204:207], v[114:117]
	v_mfma_f32_16x16x32_bf16 v[114:117], v[186:189], v[208:211], v[114:117]
	v_mfma_f32_16x16x32_bf16 v[102:105], v[150:153], v[212:215], v[102:105]
	v_mfma_f32_16x16x32_bf16 v[102:105], v[154:157], v[216:219], v[102:105]
	v_mfma_f32_16x16x32_bf16 v[98:101], v[178:181], v[212:215], v[98:101]
	v_mfma_f32_16x16x32_bf16 v[98:101], v[186:189], v[216:219], v[98:101]
	v_mfma_f32_16x16x32_bf16 v[86:89], v[150:153], v[226:229], v[86:89]
	v_mfma_f32_16x16x32_bf16 v[86:89], v[154:157], v[230:233], v[86:89]
	v_mfma_f32_16x16x32_bf16 v[82:85], v[178:181], v[226:229], v[82:85]
	v_mfma_f32_16x16x32_bf16 v[82:85], v[186:189], v[230:233], v[82:85]
	v_mfma_f32_16x16x32_bf16 v[70:73], v[150:153], v[234:237], v[70:73]
	v_mfma_f32_16x16x32_bf16 v[70:73], v[154:157], v[238:241], v[70:73]
	v_mfma_f32_16x16x32_bf16 v[66:69], v[178:181], v[234:237], v[66:69]
	v_mfma_f32_16x16x32_bf16 v[66:69], v[186:189], v[238:241], v[66:69]
	s_setprio 0
	s_barrier
	s_add_i32 s74, s75, s82
	v_lshl_add_u64 v[158:159], s[80:81], 0, v[162:163]
	s_mov_b32 m0, s74
	ds_read_b128 v[204:207], v185 offset:16384
	ds_read_b128 v[208:211], v185 offset:17408
	ds_read_b128 v[212:215], v185 offset:18432
	ds_read_b128 v[216:219], v185 offset:19456
	ds_read_b128 v[226:229], v185 offset:20480
	ds_read_b128 v[230:233], v185 offset:21504
	ds_read_b128 v[234:237], v185 offset:22528
	ds_read_b128 v[238:241], v185 offset:23552
	global_load_lds_dwordx4 v[158:159], off
	s_add_i32 m0, s74, 0x2000
	v_lshl_add_u64 v[182:183], s[80:81], 0, v[166:167]
	s_add_u32 s80, s80, s4
	s_addc_u32 s81, s81, s5
	s_add_i32 s72, s72, s82
	global_load_lds_dwordx4 v[182:183], off
	v_lshl_add_u64 v[220:221], s[80:81], 0, v[162:163]
	s_mov_b32 m0, s72
	v_lshl_add_u64 v[242:243], s[80:81], 0, v[166:167]
	global_load_lds_dwordx4 v[220:221], off
	s_add_i32 m0, s72, 0x2000
	v_lshl_add_u64 v[244:245], s[10:11], 0, v[160:161]
	global_load_lds_dwordx4 v[242:243], off
	s_mov_b32 m0, s14
	v_lshl_add_u64 v[246:247], s[10:11], 0, v[164:165]
	global_load_lds_dwordx4 v[244:245], off
	s_mov_b32 m0, s15
	s_nop 0
	global_load_lds_dwordx4 v[246:247], off
	s_waitcnt vmcnt(8)
	s_waitcnt lgkmcnt(0)
	s_barrier
	s_setprio 1
	s_waitcnt lgkmcnt(0)
	v_mfma_f32_16x16x32_bf16 v[62:65], v[134:137], v[204:207], v[62:65]
	v_mfma_f32_16x16x32_bf16 v[62:65], v[138:141], v[208:211], v[62:65]
	v_mfma_f32_16x16x32_bf16 v[58:61], v[142:145], v[204:207], v[58:61]
	v_mfma_f32_16x16x32_bf16 v[58:61], v[146:149], v[208:211], v[58:61]
	v_mfma_f32_16x16x32_bf16 v[46:49], v[134:137], v[212:215], v[46:49]
	v_mfma_f32_16x16x32_bf16 v[46:49], v[138:141], v[216:219], v[46:49]
	v_mfma_f32_16x16x32_bf16 v[42:45], v[142:145], v[212:215], v[42:45]
	v_mfma_f32_16x16x32_bf16 v[42:45], v[146:149], v[216:219], v[42:45]
	v_mfma_f32_16x16x32_bf16 v[30:33], v[134:137], v[226:229], v[30:33]
	v_mfma_f32_16x16x32_bf16 v[30:33], v[138:141], v[230:233], v[30:33]
	v_mfma_f32_16x16x32_bf16 v[26:29], v[142:145], v[226:229], v[26:29]
	v_mfma_f32_16x16x32_bf16 v[26:29], v[146:149], v[230:233], v[26:29]
	v_mfma_f32_16x16x32_bf16 v[14:17], v[134:137], v[234:237], v[14:17]
	v_mfma_f32_16x16x32_bf16 v[14:17], v[138:141], v[238:241], v[14:17]
	v_mfma_f32_16x16x32_bf16 v[10:13], v[142:145], v[234:237], v[10:13]
	v_mfma_f32_16x16x32_bf16 v[10:13], v[146:149], v[238:241], v[10:13]
	s_setprio 0
	s_setprio 1
	v_mfma_f32_16x16x32_bf16 v[54:57], v[150:153], v[204:207], v[54:57]
	v_mfma_f32_16x16x32_bf16 v[54:57], v[154:157], v[208:211], v[54:57]
	v_mfma_f32_16x16x32_bf16 v[50:53], v[178:181], v[204:207], v[50:53]
	v_mfma_f32_16x16x32_bf16 v[50:53], v[186:189], v[208:211], v[50:53]
	v_mfma_f32_16x16x32_bf16 v[38:41], v[150:153], v[212:215], v[38:41]
	v_mfma_f32_16x16x32_bf16 v[38:41], v[154:157], v[216:219], v[38:41]
	v_mfma_f32_16x16x32_bf16 v[34:37], v[178:181], v[212:215], v[34:37]
	v_mfma_f32_16x16x32_bf16 v[34:37], v[186:189], v[216:219], v[34:37]
	v_mfma_f32_16x16x32_bf16 v[22:25], v[150:153], v[226:229], v[22:25]
	v_mfma_f32_16x16x32_bf16 v[22:25], v[154:157], v[230:233], v[22:25]
	v_mfma_f32_16x16x32_bf16 v[18:21], v[178:181], v[226:229], v[18:21]
	v_mfma_f32_16x16x32_bf16 v[18:21], v[186:189], v[230:233], v[18:21]
	v_mfma_f32_16x16x32_bf16 v[6:9], v[150:153], v[234:237], v[6:9]
	v_mfma_f32_16x16x32_bf16 v[6:9], v[154:157], v[238:241], v[6:9]
	v_mfma_f32_16x16x32_bf16 v[2:5], v[178:181], v[234:237], v[2:5]
	v_mfma_f32_16x16x32_bf16 v[2:5], v[186:189], v[238:241], v[2:5]
	s_setprio 0
	s_barrier
	s_add_i32 s72, 0, 0x18000
	s_add_i32 s74, 0, 0x1c000
	v_add_u32_e32 v146, s72, v184
	v_add_u32_e32 v186, s74, v184
	ds_read_b128 v[134:137], v146
	ds_read_b128 v[138:141], v146 offset:1024
	ds_read_b128 v[142:145], v146 offset:2048
	ds_read_b128 v[146:149], v146 offset:3072
	ds_read_b128 v[150:153], v186
	ds_read_b128 v[154:157], v186 offset:1024
	ds_read_b128 v[178:181], v186 offset:2048
	ds_read_b128 v[186:189], v186 offset:3072
	s_add_u32 s10, s10, s4
	s_addc_u32 s11, s11, s5
	s_mov_b32 m0, s16
	v_lshl_add_u64 v[248:249], s[10:11], 0, v[160:161]
	ds_read_b128 v[204:207], v185 offset:32768
	ds_read_b128 v[208:211], v185 offset:33792
	ds_read_b128 v[212:215], v185 offset:34816
	ds_read_b128 v[216:219], v185 offset:35840
	ds_read_b128 v[226:229], v185 offset:36864
	ds_read_b128 v[230:233], v185 offset:37888
	ds_read_b128 v[234:237], v185 offset:38912
	ds_read_b128 v[238:241], v185 offset:39936
	global_load_lds_dwordx4 v[248:249], off
	v_lshl_add_u64 v[248:249], s[10:11], 0, v[164:165]
	s_mov_b32 m0, s17
	s_nop 0
	global_load_lds_dwordx4 v[248:249], off
	s_waitcnt vmcnt(8)
	s_waitcnt lgkmcnt(0)
	s_barrier
	s_setprio 1
	s_waitcnt lgkmcnt(0)
	v_mfma_f32_16x16x32_bf16 v[126:129], v[134:137], v[204:207], v[126:129]
	v_mfma_f32_16x16x32_bf16 v[126:129], v[138:141], v[208:211], v[126:129]
	v_mfma_f32_16x16x32_bf16 v[122:125], v[142:145], v[204:207], v[122:125]
	v_mfma_f32_16x16x32_bf16 v[122:125], v[146:149], v[208:211], v[122:125]
	v_mfma_f32_16x16x32_bf16 v[110:113], v[134:137], v[212:215], v[110:113]
	v_mfma_f32_16x16x32_bf16 v[110:113], v[138:141], v[216:219], v[110:113]
	v_mfma_f32_16x16x32_bf16 v[106:109], v[142:145], v[212:215], v[106:109]
	v_mfma_f32_16x16x32_bf16 v[106:109], v[146:149], v[216:219], v[106:109]
	v_mfma_f32_16x16x32_bf16 v[94:97], v[134:137], v[226:229], v[94:97]
	v_mfma_f32_16x16x32_bf16 v[94:97], v[138:141], v[230:233], v[94:97]
	v_mfma_f32_16x16x32_bf16 v[90:93], v[142:145], v[226:229], v[90:93]
	v_mfma_f32_16x16x32_bf16 v[90:93], v[146:149], v[230:233], v[90:93]
	v_mfma_f32_16x16x32_bf16 v[78:81], v[134:137], v[234:237], v[78:81]
	v_mfma_f32_16x16x32_bf16 v[78:81], v[138:141], v[238:241], v[78:81]
	v_mfma_f32_16x16x32_bf16 v[74:77], v[142:145], v[234:237], v[74:77]
	v_mfma_f32_16x16x32_bf16 v[74:77], v[146:149], v[238:241], v[74:77]
	s_setprio 0
	s_setprio 1
	v_mfma_f32_16x16x32_bf16 v[118:121], v[150:153], v[204:207], v[118:121]
	v_mfma_f32_16x16x32_bf16 v[118:121], v[154:157], v[208:211], v[118:121]
	v_mfma_f32_16x16x32_bf16 v[114:117], v[178:181], v[204:207], v[114:117]
	v_mfma_f32_16x16x32_bf16 v[114:117], v[186:189], v[208:211], v[114:117]
	v_mfma_f32_16x16x32_bf16 v[102:105], v[150:153], v[212:215], v[102:105]
	v_mfma_f32_16x16x32_bf16 v[102:105], v[154:157], v[216:219], v[102:105]
	v_mfma_f32_16x16x32_bf16 v[98:101], v[178:181], v[212:215], v[98:101]
	v_mfma_f32_16x16x32_bf16 v[98:101], v[186:189], v[216:219], v[98:101]
	v_mfma_f32_16x16x32_bf16 v[86:89], v[150:153], v[226:229], v[86:89]
	v_mfma_f32_16x16x32_bf16 v[86:89], v[154:157], v[230:233], v[86:89]
	v_mfma_f32_16x16x32_bf16 v[82:85], v[178:181], v[226:229], v[82:85]
	v_mfma_f32_16x16x32_bf16 v[82:85], v[186:189], v[230:233], v[82:85]
	v_mfma_f32_16x16x32_bf16 v[70:73], v[150:153], v[234:237], v[70:73]
	v_mfma_f32_16x16x32_bf16 v[70:73], v[154:157], v[238:241], v[70:73]
	v_mfma_f32_16x16x32_bf16 v[66:69], v[178:181], v[234:237], v[66:69]
	v_mfma_f32_16x16x32_bf16 v[66:69], v[186:189], v[238:241], v[66:69]
	s_setprio 0
	s_barrier
	s_add_i32 s10, s72, s82
	v_lshl_add_u64 v[158:159], v[158:159], 0, s[68:69]
	s_mov_b32 m0, s10
	ds_read_b128 v[204:207], v185 offset:49152
	ds_read_b128 v[208:211], v185 offset:50176
	ds_read_b128 v[212:215], v185 offset:51200
	ds_read_b128 v[216:219], v185 offset:52224
	ds_read_b128 v[226:229], v185 offset:53248
	ds_read_b128 v[230:233], v185 offset:54272
	ds_read_b128 v[234:237], v185 offset:55296
	ds_read_b128 v[238:241], v185 offset:56320
	global_load_lds_dwordx4 v[158:159], off
	v_lshl_add_u64 v[158:159], v[182:183], 0, s[68:69]
	s_add_i32 m0, s10, 0x2000
	s_add_i32 s10, s74, s82
	global_load_lds_dwordx4 v[158:159], off
	v_lshl_add_u64 v[158:159], v[220:221], 0, s[68:69]
	s_mov_b32 m0, s10
	s_nop 0
	global_load_lds_dwordx4 v[158:159], off
	v_lshl_add_u64 v[158:159], v[242:243], 0, s[68:69]
	s_add_i32 m0, s10, 0x2000
	s_nop 0
	global_load_lds_dwordx4 v[158:159], off
	v_lshl_add_u64 v[158:159], v[244:245], 0, s[68:69]
	s_mov_b32 m0, s79
	s_nop 0
	global_load_lds_dwordx4 v[158:159], off
	v_lshl_add_u64 v[158:159], v[246:247], 0, s[68:69]
	s_mov_b32 m0, s78
	s_nop 0
	global_load_lds_dwordx4 v[158:159], off
	s_waitcnt vmcnt(8)
	s_waitcnt lgkmcnt(0)
	s_barrier
	s_setprio 1
	s_waitcnt lgkmcnt(0)
	v_mfma_f32_16x16x32_bf16 v[62:65], v[134:137], v[204:207], v[62:65]
	v_mfma_f32_16x16x32_bf16 v[62:65], v[138:141], v[208:211], v[62:65]
	v_mfma_f32_16x16x32_bf16 v[58:61], v[142:145], v[204:207], v[58:61]
	v_mfma_f32_16x16x32_bf16 v[58:61], v[146:149], v[208:211], v[58:61]
	v_mfma_f32_16x16x32_bf16 v[46:49], v[134:137], v[212:215], v[46:49]
	v_mfma_f32_16x16x32_bf16 v[46:49], v[138:141], v[216:219], v[46:49]
	v_mfma_f32_16x16x32_bf16 v[42:45], v[142:145], v[212:215], v[42:45]
	v_mfma_f32_16x16x32_bf16 v[42:45], v[146:149], v[216:219], v[42:45]
	v_mfma_f32_16x16x32_bf16 v[30:33], v[134:137], v[226:229], v[30:33]
	v_mfma_f32_16x16x32_bf16 v[30:33], v[138:141], v[230:233], v[30:33]
	v_mfma_f32_16x16x32_bf16 v[26:29], v[142:145], v[226:229], v[26:29]
	v_mfma_f32_16x16x32_bf16 v[26:29], v[146:149], v[230:233], v[26:29]
	v_mfma_f32_16x16x32_bf16 v[14:17], v[134:137], v[234:237], v[14:17]
	v_mfma_f32_16x16x32_bf16 v[14:17], v[138:141], v[238:241], v[14:17]
	v_mfma_f32_16x16x32_bf16 v[10:13], v[142:145], v[234:237], v[10:13]
	v_mfma_f32_16x16x32_bf16 v[10:13], v[146:149], v[238:241], v[10:13]
	s_setprio 0
	s_setprio 1
	v_mfma_f32_16x16x32_bf16 v[54:57], v[150:153], v[204:207], v[54:57]
	v_mfma_f32_16x16x32_bf16 v[54:57], v[154:157], v[208:211], v[54:57]
	v_mfma_f32_16x16x32_bf16 v[50:53], v[178:181], v[204:207], v[50:53]
	v_mfma_f32_16x16x32_bf16 v[50:53], v[186:189], v[208:211], v[50:53]
	v_mfma_f32_16x16x32_bf16 v[38:41], v[150:153], v[212:215], v[38:41]
	v_mfma_f32_16x16x32_bf16 v[38:41], v[154:157], v[216:219], v[38:41]
	v_mfma_f32_16x16x32_bf16 v[34:37], v[178:181], v[212:215], v[34:37]
	v_mfma_f32_16x16x32_bf16 v[34:37], v[186:189], v[216:219], v[34:37]
	v_mfma_f32_16x16x32_bf16 v[22:25], v[150:153], v[226:229], v[22:25]
	v_mfma_f32_16x16x32_bf16 v[22:25], v[154:157], v[230:233], v[22:25]
	v_mfma_f32_16x16x32_bf16 v[18:21], v[178:181], v[226:229], v[18:21]
	v_mfma_f32_16x16x32_bf16 v[18:21], v[186:189], v[230:233], v[18:21]
	v_mfma_f32_16x16x32_bf16 v[6:9], v[150:153], v[234:237], v[6:9]
	v_mfma_f32_16x16x32_bf16 v[6:9], v[154:157], v[238:241], v[6:9]
	v_mfma_f32_16x16x32_bf16 v[2:5], v[178:181], v[234:237], v[2:5]
	v_mfma_f32_16x16x32_bf16 v[2:5], v[186:189], v[238:241], v[2:5]
	s_setprio 0
	s_add_i32 s49, s49, 2
	s_add_u32 s44, s44, 0x100
	s_addc_u32 s45, s45, 0
	s_cmp_gt_u32 s49, 13
	s_barrier
	s_cbranch_scc0 .LBB0_1658
	s_and_b64 vcc, exec, s[24:25]
	s_cbranch_vccz .LBB0_1661
	s_barrier

.LBB0_1766:
	s_add_i32 s82, s26, 2
	s_add_u32 s74, s24, 0x80
	s_addc_u32 s27, s25, 0
	s_add_i32 s85, 0, 0x10000
	s_cmp_eq_u32 s19, s26
	s_cselect_b32 s27, s21, s27
	s_cselect_b32 s26, s20, s74
	v_add_u32_e32 v148, s85, v152
	s_cselect_b32 s75, s23, s29
	s_cselect_b32 s74, s22, s28
	s_add_i32 s86, 0, 0x14000
	ds_read_b128 v[130:133], v148
	ds_read_b128 v[144:147], v148 offset:1024
	ds_read_b128 v[154:157], v148 offset:2048
	ds_read_b128 v[158:161], v148 offset:3072
	v_add_u32_e32 v148, s86, v152
	ds_read_b128 v[162:165], v148
	ds_read_b128 v[166:169], v148 offset:1024
	ds_read_b128 v[170:173], v148 offset:2048
	ds_read_b128 v[174:177], v148 offset:3072
	v_lshl_add_u64 v[148:149], s[24:25], 0, v[140:141]
	s_add_i32 m0, s34, 0xc000
	ds_read_b128 v[178:181], v153
	ds_read_b128 v[182:185], v153 offset:1024
	ds_read_b128 v[186:189], v153 offset:2048
	ds_read_b128 v[204:207], v153 offset:3072
	ds_read_b128 v[208:211], v153 offset:4096
	ds_read_b128 v[212:215], v153 offset:5120
	ds_read_b128 v[216:219], v153 offset:6144
	ds_read_b128 v[226:229], v153 offset:7168
	global_load_lds_dwordx4 v[148:149], off
	v_lshl_add_u64 v[148:149], s[24:25], 0, v[142:143]
	s_add_i32 m0, s34, 0xe000
	s_nop 0
	global_load_lds_dwordx4 v[148:149], off
	s_waitcnt vmcnt(8)
	s_waitcnt lgkmcnt(0)
	s_barrier
	s_setprio 1
	s_waitcnt lgkmcnt(0)
	v_mfma_f32_16x16x32_bf16 v[126:129], v[130:133], v[178:181], v[126:129]
	v_mfma_f32_16x16x32_bf16 v[126:129], v[144:147], v[182:185], v[126:129]
	v_mfma_f32_16x16x32_bf16 v[122:125], v[154:157], v[178:181], v[122:125]
	v_mfma_f32_16x16x32_bf16 v[122:125], v[158:161], v[182:185], v[122:125]
	v_mfma_f32_16x16x32_bf16 v[110:113], v[130:133], v[186:189], v[110:113]
	v_mfma_f32_16x16x32_bf16 v[110:113], v[144:147], v[204:207], v[110:113]
	v_mfma_f32_16x16x32_bf16 v[106:109], v[154:157], v[186:189], v[106:109]
	v_mfma_f32_16x16x32_bf16 v[106:109], v[158:161], v[204:207], v[106:109]
	v_mfma_f32_16x16x32_bf16 v[94:97], v[130:133], v[208:211], v[94:97]
	v_mfma_f32_16x16x32_bf16 v[94:97], v[144:147], v[212:215], v[94:97]
	v_mfma_f32_16x16x32_bf16 v[90:93], v[154:157], v[208:211], v[90:93]
	v_mfma_f32_16x16x32_bf16 v[90:93], v[158:161], v[212:215], v[90:93]
	v_mfma_f32_16x16x32_bf16 v[78:81], v[130:133], v[216:219], v[78:81]
	v_mfma_f32_16x16x32_bf16 v[78:81], v[144:147], v[226:229], v[78:81]
	v_mfma_f32_16x16x32_bf16 v[74:77], v[154:157], v[216:219], v[74:77]
	v_mfma_f32_16x16x32_bf16 v[74:77], v[158:161], v[226:229], v[74:77]
	s_setprio 0
	s_setprio 1
	v_mfma_f32_16x16x32_bf16 v[118:121], v[162:165], v[178:181], v[118:121]
	v_mfma_f32_16x16x32_bf16 v[118:121], v[166:169], v[182:185], v[118:121]
	v_mfma_f32_16x16x32_bf16 v[114:117], v[170:173], v[178:181], v[114:117]
	v_mfma_f32_16x16x32_bf16 v[114:117], v[174:177], v[182:185], v[114:117]
	v_mfma_f32_16x16x32_bf16 v[102:105], v[162:165], v[186:189], v[102:105]
	v_mfma_f32_16x16x32_bf16 v[102:105], v[166:169], v[204:207], v[102:105]
	v_mfma_f32_16x16x32_bf16 v[98:101], v[170:173], v[186:189], v[98:101]
	v_mfma_f32_16x16x32_bf16 v[98:101], v[174:177], v[204:207], v[98:101]
	v_mfma_f32_16x16x32_bf16 v[86:89], v[162:165], v[208:211], v[86:89]
	v_mfma_f32_16x16x32_bf16 v[86:89], v[166:169], v[212:215], v[86:89]
	v_mfma_f32_16x16x32_bf16 v[82:85], v[170:173], v[208:211], v[82:85]
	v_mfma_f32_16x16x32_bf16 v[82:85], v[174:177], v[212:215], v[82:85]
	v_mfma_f32_16x16x32_bf16 v[70:73], v[162:165], v[216:219], v[70:73]
	v_mfma_f32_16x16x32_bf16 v[70:73], v[166:169], v[226:229], v[70:73]
	v_mfma_f32_16x16x32_bf16 v[66:69], v[170:173], v[216:219], v[66:69]
	v_mfma_f32_16x16x32_bf16 v[66:69], v[174:177], v[226:229], v[66:69]
	s_setprio 0
	s_barrier
	s_add_i32 s85, s85, s33
	v_lshl_add_u64 v[148:149], s[74:75], 0, v[190:191]
	s_mov_b32 m0, s85
	ds_read_b128 v[178:181], v153 offset:16384
	ds_read_b128 v[182:185], v153 offset:17408
	ds_read_b128 v[186:189], v153 offset:18432
	ds_read_b128 v[204:207], v153 offset:19456
	ds_read_b128 v[208:211], v153 offset:20480
	ds_read_b128 v[212:215], v153 offset:21504
	ds_read_b128 v[216:219], v153 offset:22528
	ds_read_b128 v[226:229], v153 offset:23552
	global_load_lds_dwordx4 v[148:149], off
	s_add_i32 m0, s85, 0x2000
	v_lshl_add_u64 v[220:221], s[74:75], 0, v[138:139]
	s_add_u32 s74, s74, s8
	s_addc_u32 s75, s75, s9
	s_add_i32 s85, s86, s33
	global_load_lds_dwordx4 v[220:221], off
	v_lshl_add_u64 v[230:231], s[74:75], 0, v[190:191]
	s_mov_b32 m0, s85
	v_lshl_add_u64 v[232:233], s[74:75], 0, v[138:139]
	global_load_lds_dwordx4 v[230:231], off
	s_add_i32 m0, s85, 0x2000
	v_lshl_add_u64 v[234:235], s[26:27], 0, v[134:135]
	global_load_lds_dwordx4 v[232:233], off
	s_mov_b32 m0, s34
	v_lshl_add_u64 v[236:237], s[26:27], 0, v[136:137]
	global_load_lds_dwordx4 v[234:235], off
	s_mov_b32 m0, s35
	s_nop 0
	global_load_lds_dwordx4 v[236:237], off
	s_waitcnt vmcnt(8)
	s_waitcnt lgkmcnt(0)
	s_barrier
	s_setprio 1
	s_waitcnt lgkmcnt(0)
	v_mfma_f32_16x16x32_bf16 v[62:65], v[130:133], v[178:181], v[62:65]
	v_mfma_f32_16x16x32_bf16 v[62:65], v[144:147], v[182:185], v[62:65]
	v_mfma_f32_16x16x32_bf16 v[58:61], v[154:157], v[178:181], v[58:61]
	v_mfma_f32_16x16x32_bf16 v[58:61], v[158:161], v[182:185], v[58:61]
	v_mfma_f32_16x16x32_bf16 v[46:49], v[130:133], v[186:189], v[46:49]
	v_mfma_f32_16x16x32_bf16 v[46:49], v[144:147], v[204:207], v[46:49]
	v_mfma_f32_16x16x32_bf16 v[42:45], v[154:157], v[186:189], v[42:45]
	v_mfma_f32_16x16x32_bf16 v[42:45], v[158:161], v[204:207], v[42:45]
	v_mfma_f32_16x16x32_bf16 v[30:33], v[130:133], v[208:211], v[30:33]
	v_mfma_f32_16x16x32_bf16 v[30:33], v[144:147], v[212:215], v[30:33]
	v_mfma_f32_16x16x32_bf16 v[26:29], v[154:157], v[208:211], v[26:29]
	v_mfma_f32_16x16x32_bf16 v[26:29], v[158:161], v[212:215], v[26:29]
	v_mfma_f32_16x16x32_bf16 v[14:17], v[130:133], v[216:219], v[14:17]
	v_mfma_f32_16x16x32_bf16 v[14:17], v[144:147], v[226:229], v[14:17]
	v_mfma_f32_16x16x32_bf16 v[10:13], v[154:157], v[216:219], v[10:13]
	v_mfma_f32_16x16x32_bf16 v[10:13], v[158:161], v[226:229], v[10:13]
	s_setprio 0
	s_setprio 1
	v_mfma_f32_16x16x32_bf16 v[54:57], v[162:165], v[178:181], v[54:57]
	v_mfma_f32_16x16x32_bf16 v[54:57], v[166:169], v[182:185], v[54:57]
	v_mfma_f32_16x16x32_bf16 v[50:53], v[170:173], v[178:181], v[50:53]
	v_mfma_f32_16x16x32_bf16 v[50:53], v[174:177], v[182:185], v[50:53]
	v_mfma_f32_16x16x32_bf16 v[38:41], v[162:165], v[186:189], v[38:41]
	v_mfma_f32_16x16x32_bf16 v[38:41], v[166:169], v[204:207], v[38:41]
	v_mfma_f32_16x16x32_bf16 v[34:37], v[170:173], v[186:189], v[34:37]
	v_mfma_f32_16x16x32_bf16 v[34:37], v[174:177], v[204:207], v[34:37]
	v_mfma_f32_16x16x32_bf16 v[22:25], v[162:165], v[208:211], v[22:25]
	v_mfma_f32_16x16x32_bf16 v[22:25], v[166:169], v[212:215], v[22:25]
	v_mfma_f32_16x16x32_bf16 v[18:21], v[170:173], v[208:211], v[18:21]
	v_mfma_f32_16x16x32_bf16 v[18:21], v[174:177], v[212:215], v[18:21]
	v_mfma_f32_16x16x32_bf16 v[6:9], v[162:165], v[216:219], v[6:9]
	v_mfma_f32_16x16x32_bf16 v[6:9], v[166:169], v[226:229], v[6:9]
	v_mfma_f32_16x16x32_bf16 v[2:5], v[170:173], v[216:219], v[2:5]
	v_mfma_f32_16x16x32_bf16 v[2:5], v[174:177], v[226:229], v[2:5]
	s_setprio 0
	s_barrier
	s_add_i32 s74, 0, 0x18000
	s_add_i32 s75, 0, 0x1c000
	v_add_u32_e32 v158, s74, v152
	v_add_u32_e32 v174, s75, v152
	ds_read_b128 v[130:133], v158
	ds_read_b128 v[144:147], v158 offset:1024
	ds_read_b128 v[154:157], v158 offset:2048
	ds_read_b128 v[158:161], v158 offset:3072
	ds_read_b128 v[162:165], v174
	ds_read_b128 v[166:169], v174 offset:1024
	ds_read_b128 v[170:173], v174 offset:2048
	ds_read_b128 v[174:177], v174 offset:3072
	s_add_u32 s26, s26, s8
	s_addc_u32 s27, s27, s9
	s_mov_b32 m0, s36
	v_lshl_add_u64 v[238:239], s[26:27], 0, v[134:135]
	ds_read_b128 v[178:181], v153 offset:32768
	ds_read_b128 v[182:185], v153 offset:33792
	ds_read_b128 v[186:189], v153 offset:34816
	ds_read_b128 v[204:207], v153 offset:35840
	ds_read_b128 v[208:211], v153 offset:36864
	ds_read_b128 v[212:215], v153 offset:37888
	ds_read_b128 v[216:219], v153 offset:38912
	ds_read_b128 v[226:229], v153 offset:39936
	global_load_lds_dwordx4 v[238:239], off
	v_lshl_add_u64 v[238:239], s[26:27], 0, v[136:137]
	s_mov_b32 m0, s37
	s_nop 0
	global_load_lds_dwordx4 v[238:239], off
	s_waitcnt vmcnt(8)
	s_waitcnt lgkmcnt(0)
	s_barrier
	s_setprio 1
	s_waitcnt lgkmcnt(0)
	v_mfma_f32_16x16x32_bf16 v[126:129], v[130:133], v[178:181], v[126:129]
	v_mfma_f32_16x16x32_bf16 v[126:129], v[144:147], v[182:185], v[126:129]
	v_mfma_f32_16x16x32_bf16 v[122:125], v[154:157], v[178:181], v[122:125]
	v_mfma_f32_16x16x32_bf16 v[122:125], v[158:161], v[182:185], v[122:125]
	v_mfma_f32_16x16x32_bf16 v[110:113], v[130:133], v[186:189], v[110:113]
	v_mfma_f32_16x16x32_bf16 v[110:113], v[144:147], v[204:207], v[110:113]
	v_mfma_f32_16x16x32_bf16 v[106:109], v[154:157], v[186:189], v[106:109]
	v_mfma_f32_16x16x32_bf16 v[106:109], v[158:161], v[204:207], v[106:109]
	v_mfma_f32_16x16x32_bf16 v[94:97], v[130:133], v[208:211], v[94:97]
	v_mfma_f32_16x16x32_bf16 v[94:97], v[144:147], v[212:215], v[94:97]
	v_mfma_f32_16x16x32_bf16 v[90:93], v[154:157], v[208:211], v[90:93]
	v_mfma_f32_16x16x32_bf16 v[90:93], v[158:161], v[212:215], v[90:93]
	v_mfma_f32_16x16x32_bf16 v[78:81], v[130:133], v[216:219], v[78:81]
	v_mfma_f32_16x16x32_bf16 v[78:81], v[144:147], v[226:229], v[78:81]
	v_mfma_f32_16x16x32_bf16 v[74:77], v[154:157], v[216:219], v[74:77]
	v_mfma_f32_16x16x32_bf16 v[74:77], v[158:161], v[226:229], v[74:77]
	s_setprio 0
	s_setprio 1
	v_mfma_f32_16x16x32_bf16 v[118:121], v[162:165], v[178:181], v[118:121]
	v_mfma_f32_16x16x32_bf16 v[118:121], v[166:169], v[182:185], v[118:121]
	v_mfma_f32_16x16x32_bf16 v[114:117], v[170:173], v[178:181], v[114:117]
	v_mfma_f32_16x16x32_bf16 v[114:117], v[174:177], v[182:185], v[114:117]
	v_mfma_f32_16x16x32_bf16 v[102:105], v[162:165], v[186:189], v[102:105]
	v_mfma_f32_16x16x32_bf16 v[102:105], v[166:169], v[204:207], v[102:105]
	v_mfma_f32_16x16x32_bf16 v[98:101], v[170:173], v[186:189], v[98:101]
	v_mfma_f32_16x16x32_bf16 v[98:101], v[174:177], v[204:207], v[98:101]
	v_mfma_f32_16x16x32_bf16 v[86:89], v[162:165], v[208:211], v[86:89]
	v_mfma_f32_16x16x32_bf16 v[86:89], v[166:169], v[212:215], v[86:89]
	v_mfma_f32_16x16x32_bf16 v[82:85], v[170:173], v[208:211], v[82:85]
	v_mfma_f32_16x16x32_bf16 v[82:85], v[174:177], v[212:215], v[82:85]
	v_mfma_f32_16x16x32_bf16 v[70:73], v[162:165], v[216:219], v[70:73]
	v_mfma_f32_16x16x32_bf16 v[70:73], v[166:169], v[226:229], v[70:73]
	v_mfma_f32_16x16x32_bf16 v[66:69], v[170:173], v[216:219], v[66:69]
	v_mfma_f32_16x16x32_bf16 v[66:69], v[174:177], v[226:229], v[66:69]
	s_setprio 0
	s_barrier
	s_add_i32 s26, s74, s33
	v_lshl_add_u64 v[148:149], v[148:149], 0, s[68:69]
	s_mov_b32 m0, s26
	ds_read_b128 v[178:181], v153 offset:49152
	ds_read_b128 v[182:185], v153 offset:50176
	ds_read_b128 v[186:189], v153 offset:51200
	ds_read_b128 v[204:207], v153 offset:52224
	ds_read_b128 v[208:211], v153 offset:53248
	ds_read_b128 v[212:215], v153 offset:54272
	ds_read_b128 v[216:219], v153 offset:55296
	ds_read_b128 v[226:229], v153 offset:56320
	global_load_lds_dwordx4 v[148:149], off
	v_lshl_add_u64 v[148:149], v[220:221], 0, s[68:69]
	s_add_i32 m0, s26, 0x2000
	s_add_i32 s26, s75, s33
	global_load_lds_dwordx4 v[148:149], off
	v_lshl_add_u64 v[148:149], v[230:231], 0, s[68:69]
	s_mov_b32 m0, s26
	s_nop 0
	global_load_lds_dwordx4 v[148:149], off
	v_lshl_add_u64 v[148:149], v[232:233], 0, s[68:69]
	s_add_i32 m0, s26, 0x2000
	s_nop 0
	global_load_lds_dwordx4 v[148:149], off
	v_lshl_add_u64 v[148:149], v[234:235], 0, s[68:69]
	s_mov_b32 m0, s59
	s_nop 0
	global_load_lds_dwordx4 v[148:149], off
	v_lshl_add_u64 v[148:149], v[236:237], 0, s[68:69]
	s_mov_b32 m0, s64
	s_nop 0
	global_load_lds_dwordx4 v[148:149], off
	s_waitcnt vmcnt(8)
	s_waitcnt lgkmcnt(0)
	s_barrier
	s_setprio 1
	s_waitcnt lgkmcnt(0)
	v_mfma_f32_16x16x32_bf16 v[62:65], v[130:133], v[178:181], v[62:65]
	v_mfma_f32_16x16x32_bf16 v[62:65], v[144:147], v[182:185], v[62:65]
	v_mfma_f32_16x16x32_bf16 v[58:61], v[154:157], v[178:181], v[58:61]
	v_mfma_f32_16x16x32_bf16 v[58:61], v[158:161], v[182:185], v[58:61]
	v_mfma_f32_16x16x32_bf16 v[46:49], v[130:133], v[186:189], v[46:49]
	v_mfma_f32_16x16x32_bf16 v[46:49], v[144:147], v[204:207], v[46:49]
	v_mfma_f32_16x16x32_bf16 v[42:45], v[154:157], v[186:189], v[42:45]
	v_mfma_f32_16x16x32_bf16 v[42:45], v[158:161], v[204:207], v[42:45]
	v_mfma_f32_16x16x32_bf16 v[30:33], v[130:133], v[208:211], v[30:33]
	v_mfma_f32_16x16x32_bf16 v[30:33], v[144:147], v[212:215], v[30:33]
	v_mfma_f32_16x16x32_bf16 v[26:29], v[154:157], v[208:211], v[26:29]
	v_mfma_f32_16x16x32_bf16 v[26:29], v[158:161], v[212:215], v[26:29]
	v_mfma_f32_16x16x32_bf16 v[14:17], v[130:133], v[216:219], v[14:17]
	v_mfma_f32_16x16x32_bf16 v[14:17], v[144:147], v[226:229], v[14:17]
	v_mfma_f32_16x16x32_bf16 v[10:13], v[154:157], v[216:219], v[10:13]
	v_mfma_f32_16x16x32_bf16 v[10:13], v[158:161], v[226:229], v[10:13]
	s_setprio 0
	s_setprio 1
	v_mfma_f32_16x16x32_bf16 v[54:57], v[162:165], v[178:181], v[54:57]
	v_mfma_f32_16x16x32_bf16 v[54:57], v[166:169], v[182:185], v[54:57]
	v_mfma_f32_16x16x32_bf16 v[50:53], v[170:173], v[178:181], v[50:53]
	v_mfma_f32_16x16x32_bf16 v[50:53], v[174:177], v[182:185], v[50:53]
	v_mfma_f32_16x16x32_bf16 v[38:41], v[162:165], v[186:189], v[38:41]
	v_mfma_f32_16x16x32_bf16 v[38:41], v[166:169], v[204:207], v[38:41]
	v_mfma_f32_16x16x32_bf16 v[34:37], v[170:173], v[186:189], v[34:37]
	v_mfma_f32_16x16x32_bf16 v[34:37], v[174:177], v[204:207], v[34:37]
	v_mfma_f32_16x16x32_bf16 v[22:25], v[162:165], v[208:211], v[22:25]
	v_mfma_f32_16x16x32_bf16 v[22:25], v[166:169], v[212:215], v[22:25]
	v_mfma_f32_16x16x32_bf16 v[18:21], v[170:173], v[208:211], v[18:21]
	v_mfma_f32_16x16x32_bf16 v[18:21], v[174:177], v[212:215], v[18:21]
	v_mfma_f32_16x16x32_bf16 v[6:9], v[162:165], v[216:219], v[6:9]
	v_mfma_f32_16x16x32_bf16 v[6:9], v[166:169], v[226:229], v[6:9]
	v_mfma_f32_16x16x32_bf16 v[2:5], v[170:173], v[216:219], v[2:5]
	v_mfma_f32_16x16x32_bf16 v[2:5], v[174:177], v[226:229], v[2:5]
	s_setprio 0
	s_add_u32 s24, s24, 0x100
	s_addc_u32 s25, s25, 0
	s_add_u32 s28, s28, 0x100
	s_addc_u32 s29, s29, 0
	s_cmp_ge_i32 s82, s81
	s_mov_b32 s26, s82
	s_barrier
	s_cbranch_scc0 .LBB0_1766
	s_and_b64 vcc, exec, s[14:15]
	s_cbranch_vccz .LBB0_1769
	s_barrier
